# D1 on down-L0 skinny: 11 of 16 second-half A loads hoisted to chunk top (free VGPRs), regenerated compute block with counted waits
# baseline (speedup 1.0000x reference)
.LBB0_887:
	s_getreg_b32 s6, hwreg(HW_REG_HW_ID, 0, 6)
	s_and_b32 s6, s6, 63
	s_lshl_b32 s6, s6, 2
	s_add_i32 s6, s6, 0
	s_add_i32 s6, s6, 0x23e00
	v_mov_b32_e32 v138, s6
	flat_load_dword v4, v[138:139] sc0 sc1
	s_waitcnt vmcnt(0)
	s_movk_i32 s6, 0x1000
	s_lshl_b32 s45, s30, 5
	s_ashr_i32 s31, s6, 10
	v_mov_b32_e32 v35, 0
	v_mov_b32_e32 v34, 0
	v_mov_b32_e32 v33, 0
	v_mov_b32_e32 v32, 0
	v_mov_b32_e32 v31, 0
	v_mov_b32_e32 v30, 0
	v_mov_b32_e32 v29, 0
	v_mov_b32_e32 v28, 0
	v_mov_b32_e32 v27, 0
	v_mov_b32_e32 v26, 0
	v_mov_b32_e32 v25, 0
	v_mov_b32_e32 v24, 0
	v_mov_b32_e32 v23, 0
	v_mov_b32_e32 v22, 0
	v_mov_b32_e32 v21, 0
	v_mov_b32_e32 v20, 0
	v_mov_b32_e32 v19, 0
	v_mov_b32_e32 v18, 0
	v_mov_b32_e32 v17, 0
	v_mov_b32_e32 v16, 0
	v_mov_b32_e32 v15, 0
	v_mov_b32_e32 v14, 0
	v_mov_b32_e32 v13, 0
	v_mov_b32_e32 v12, 0
	v_mov_b32_e32 v11, 0
	v_mov_b32_e32 v10, 0
	v_mov_b32_e32 v9, 0
	v_mov_b32_e32 v8, 0
	v_mov_b32_e32 v7, 0
	v_mov_b32_e32 v6, 0
	v_mov_b32_e32 v5, 0
	s_cmp_lt_i32 s31, 1
	s_waitcnt lgkmcnt(0)
	v_readfirstlane_b32 s7, v4
	s_nop 1
	v_lshl_add_u32 v138, s7, 6, v217
	v_ashrrev_i32_e32 v68, 7, v138
	v_ashrrev_i32_e32 v172, 6, v138
	v_and_b32_e32 v140, -2, v68
	v_and_b32_e32 v173, 3, v172
	v_ashrrev_i32_e32 v141, 31, v140
	v_mov_b32_e32 v4, 0
	s_cbranch_scc1 .LBB0_892
	v_add_u32_e32 v8, 0x200, v138
	v_add_u32_e32 v12, 0x600, v138
	v_add_u32_e32 v16, 0xa00, v138
	v_add_u32_e32 v20, 0xe00, v138
	v_lshlrev_b32_e32 v4, 4, v138
	v_ashrrev_i32_e32 v22, 7, v8
	v_add_u32_e32 v10, 0x400, v138
	v_ashrrev_i32_e32 v24, 7, v12
	v_add_u32_e32 v14, 0x800, v138
	v_ashrrev_i32_e32 v26, 7, v16
	v_add_u32_e32 v18, 0xc00, v138
	v_ashrrev_i32_e32 v28, 7, v20
	v_and_b32_e32 v132, 0x7f0, v4
	v_add_u32_e32 v8, s45, v22
	v_ashrrev_i32_e32 v23, 7, v10
	v_add_u32_e32 v12, s45, v24
	v_ashrrev_i32_e32 v25, 7, v14
	v_add_u32_e32 v16, s45, v26
	v_ashrrev_i32_e32 v27, 7, v18
	v_add_u32_e32 v20, s45, v28
	v_lshl_add_u64 v[4:5], s[10:11], 0, v[132:133]
	v_add_u32_e32 v6, s45, v68
	v_mad_i64_i32 v[8:9], s[34:35], v8, s6, 0
	v_add_u32_e32 v10, s45, v23
	v_mad_i64_i32 v[12:13], s[34:35], v12, s6, 0
	v_add_u32_e32 v14, s45, v25
	v_mad_i64_i32 v[16:17], s[34:35], v16, s6, 0
	v_add_u32_e32 v18, s45, v27
	v_mad_i64_i32 v[20:21], s[34:35], v20, s6, 0
	v_mad_i64_i32 v[6:7], s[34:35], v6, s6, 0
	v_mad_i64_i32 v[10:11], s[34:35], v10, s6, 0
	v_mad_i64_i32 v[14:15], s[34:35], v14, s6, 0
	v_mad_i64_i32 v[18:19], s[34:35], v18, s6, 0
	v_lshl_add_u64 v[20:21], v[20:21], 1, v[4:5]
	v_lshl_add_u64 v[16:17], v[16:17], 1, v[4:5]
	v_lshl_add_u64 v[12:13], v[12:13], 1, v[4:5]
	v_lshl_add_u64 v[8:9], v[8:9], 1, v[4:5]
	v_lshl_add_u64 v[18:19], v[18:19], 1, v[4:5]
	global_load_dwordx4 v[64:67], v[20:21], off
	global_load_dwordx4 v[60:63], v[18:19], off
	v_lshl_add_u64 v[14:15], v[14:15], 1, v[4:5]
	global_load_dwordx4 v[56:59], v[16:17], off
	global_load_dwordx4 v[52:55], v[14:15], off
	v_lshl_add_u64 v[10:11], v[10:11], 1, v[4:5]
	global_load_dwordx4 v[48:51], v[12:13], off
	global_load_dwordx4 v[44:47], v[10:11], off
	v_lshl_add_u64 v[4:5], v[6:7], 1, v[4:5]
	global_load_dwordx4 v[40:43], v[8:9], off
	global_load_dwordx4 v[36:39], v[4:5], off
	s_ashr_i32 s7, s6, 31
	v_add_u32_e32 v16, s12, v68
	v_and_b32_e32 v4, 0x7f, v138
	s_ashr_i32 s36, s6, 4
	v_add_u32_e32 v6, 0, v132
	s_lshl_b32 s46, s6, 1
	v_ashrrev_i32_e32 v17, 31, v16
	v_lshlrev_b32_e32 v132, 4, v4
	s_lshr_b64 s[6:7], s[6:7], 31
	v_mad_u64_u32 v[4:5], s[34:35], s46, v16, v[132:133]
	v_mul_lo_u32 v17, s46, v17
	v_mul_lo_u32 v16, s6, v16
	v_add3_u32 v5, v16, v5, v17
	v_add_u32_e32 v16, s12, v22
	v_ashrrev_i32_e32 v17, 31, v16
	v_lshl_add_u64 v[142:143], v[4:5], 0, s[22:23]
	v_mad_u64_u32 v[4:5], s[34:35], s46, v16, v[132:133]
	v_mul_lo_u32 v16, s6, v16
	v_mul_lo_u32 v17, s46, v17
	v_add3_u32 v5, v16, v5, v17
	v_add_u32_e32 v16, s12, v23
	v_ashrrev_i32_e32 v17, 31, v16
	v_lshl_add_u64 v[144:145], v[4:5], 0, s[22:23]
	v_mad_u64_u32 v[4:5], s[34:35], s46, v16, v[132:133]
	v_mul_lo_u32 v16, s6, v16
	v_mul_lo_u32 v17, s46, v17
	v_add3_u32 v5, v16, v5, v17
	v_add_u32_e32 v16, s12, v24
	v_ashrrev_i32_e32 v17, 31, v16
	v_lshl_add_u64 v[146:147], v[4:5], 0, s[22:23]
	v_mad_u64_u32 v[4:5], s[34:35], s46, v16, v[132:133]
	v_mul_lo_u32 v16, s6, v16
	v_mul_lo_u32 v17, s46, v17
	v_add3_u32 v5, v16, v5, v17
	v_add_u32_e32 v16, s12, v25
	v_ashrrev_i32_e32 v17, 31, v16
	v_lshl_add_u64 v[148:149], v[4:5], 0, s[22:23]
	v_mad_u64_u32 v[4:5], s[34:35], s46, v16, v[132:133]
	v_mul_lo_u32 v16, s6, v16
	v_mul_lo_u32 v17, s46, v17
	v_add3_u32 v5, v16, v5, v17
	v_add_u32_e32 v16, s12, v26
	v_ashrrev_i32_e32 v17, 31, v16
	v_lshl_add_u64 v[150:151], v[4:5], 0, s[22:23]
	v_mad_u64_u32 v[4:5], s[34:35], s46, v16, v[132:133]
	v_mul_lo_u32 v16, s6, v16
	v_mul_lo_u32 v17, s46, v17
	v_add3_u32 v5, v16, v5, v17
	v_add_u32_e32 v16, s12, v27
	v_ashrrev_i32_e32 v17, 31, v16
	v_lshl_add_u64 v[152:153], v[4:5], 0, s[22:23]
	v_mad_u64_u32 v[4:5], s[34:35], s46, v16, v[132:133]
	v_mul_lo_u32 v16, s6, v16
	v_mul_lo_u32 v17, s46, v17
	v_add3_u32 v5, v16, v5, v17
	v_add_u32_e32 v16, s12, v28
	v_ashrrev_i32_e32 v17, 31, v16
	v_lshl_add_u64 v[154:155], v[4:5], 0, s[22:23]
	v_mad_u64_u32 v[4:5], s[34:35], s46, v16, v[132:133]
	v_mul_lo_u32 v16, s6, v16
	v_mul_lo_u32 v17, s46, v17
	v_add3_u32 v5, v16, v5, v17
	v_lshl_add_u64 v[156:157], v[4:5], 0, s[22:23]
	v_mad_i64_i32 v[4:5], s[6:7], s36, v140, 0
	v_lshlrev_b64 v[4:5], 10, v[4:5]
	v_lshlrev_b32_e32 v16, 8, v138
	v_or_b32_e32 v4, v136, v4
	v_and_b32_e32 v132, 0xc000, v16
	v_lshl_add_u64 v[158:159], v[4:5], 0, v[132:133]
	v_lshlrev_b64 v[4:5], 10, v[140:141]
	s_ashr_i32 s37, s36, 31
	v_lshl_add_u64 v[4:5], v[4:5], 0, s[24:25]
	v_mul_lo_u32 v16, v5, s36
	v_mul_lo_u32 v17, v4, s37
	v_mad_u64_u32 v[4:5], s[6:7], v4, s36, 0
	v_add3_u32 v5, v5, v17, v16
	v_or_b32_e32 v4, v136, v4
	v_mul_lo_u32 v7, v68, s3
	v_mul_lo_u32 v8, v22, s3
	v_mul_lo_u32 v9, v23, s3
	v_mul_lo_u32 v10, v24, s3
	v_mul_lo_u32 v11, v25, s3
	v_mul_lo_u32 v12, v26, s3
	v_mul_lo_u32 v13, v27, s3
	v_mul_lo_u32 v14, v28, s3
	v_lshl_or_b32 v15, v173, 9, v166
	v_lshl_add_u64 v[160:161], v[4:5], 0, v[132:133]
	v_mov_b32_e32 v4, 0
	s_mov_b32 s6, 0
	v_add_u32_e32 v132, v6, v7
	v_add_u32_e32 v141, v6, v8
	v_add_u32_e32 v174, v6, v9
	v_add_u32_e32 v175, v6, v10
	v_add_u32_e32 v176, v6, v11
	v_add_u32_e32 v177, v6, v12
	v_add_u32_e32 v178, v6, v13
	v_add_u32_e32 v179, v6, v14
	v_add_u32_e32 v180, v137, v15
	v_mov_b32_e32 v5, v4
	v_mov_b32_e32 v6, v4
	v_mov_b32_e32 v7, v4
	v_mov_b32_e32 v8, v4
	v_mov_b32_e32 v9, v4
	v_mov_b32_e32 v10, v4
	v_mov_b32_e32 v11, v4
	v_mov_b32_e32 v12, v4
	v_mov_b32_e32 v13, v4
	v_mov_b32_e32 v14, v4
	v_mov_b32_e32 v15, v4
	v_mov_b32_e32 v16, v4
	v_mov_b32_e32 v17, v4
	v_mov_b32_e32 v18, v4
	v_mov_b32_e32 v19, v4
	v_mov_b32_e32 v20, v4
	v_mov_b32_e32 v21, v4
	v_mov_b32_e32 v22, v4
	v_mov_b32_e32 v23, v4
	v_mov_b32_e32 v24, v4
	v_mov_b32_e32 v25, v4
	v_mov_b32_e32 v26, v4
	v_mov_b32_e32 v27, v4
	v_mov_b32_e32 v28, v4
	v_mov_b32_e32 v29, v4
	v_mov_b32_e32 v30, v4
	v_mov_b32_e32 v31, v4
	v_mov_b32_e32 v32, v4
	v_mov_b32_e32 v33, v4
	v_mov_b32_e32 v34, v4
	v_mov_b32_e32 v35, v4
	s_add_u32 s98, s82, s38
	s_addc_u32 s99, s83, 0
	s_branch .LBB0_890
.LBB0_889:
	v_lshl_add_u64 v[142:143], v[142:143], 0, s[26:27]
	v_lshl_add_u64 v[144:145], v[144:145], 0, s[26:27]
	v_lshl_add_u64 v[146:147], v[146:147], 0, s[26:27]
	v_lshl_add_u64 v[148:149], v[148:149], 0, s[26:27]
	v_lshl_add_u64 v[150:151], v[150:151], 0, s[26:27]
	v_lshl_add_u64 v[152:153], v[152:153], 0, s[26:27]
	v_lshl_add_u64 v[154:155], v[154:155], 0, s[26:27]
	v_lshl_add_u64 v[156:157], v[156:157], 0, s[26:27]
	v_lshl_add_u64 v[158:159], v[158:159], 0, s[28:29]
	v_lshl_add_u64 v[160:161], v[160:161], 0, s[28:29]
	ds_read_b128 v[182:185], v180
	ds_read_b128 v[186:189], v180 offset:32
	s_waitcnt vmcnt(20) lgkmcnt(1)
	v_mfma_f32_32x32x16_bf16 v[4:19], v[182:185], v[124:127], v[4:19]
	s_waitcnt vmcnt(14)
	v_mfma_f32_32x32x16_bf16 v[20:35], v[182:185], v[128:131], v[20:35]
	ds_read_b128 v[182:185], v180 offset:64
	global_load_dwordx4 v[124:127], v254, s[98:99] offset:1024
	global_load_dwordx4 v[128:131], v245, s[98:99] offset:2048
	s_waitcnt vmcnt(28) lgkmcnt(1)
	v_mfma_f32_32x32x16_bf16 v[4:19], v[186:189], v[116:119], v[4:19]
	s_waitcnt vmcnt(26)
	v_mfma_f32_32x32x16_bf16 v[20:35], v[186:189], v[120:123], v[20:35]
	ds_read_b128 v[186:189], v180 offset:96
	global_load_dwordx4 v[116:119], v254, s[98:99] offset:2048
	global_load_dwordx4 v[120:123], v245, s[98:99] offset:3072
	s_waitcnt vmcnt(29) lgkmcnt(1)
	v_mfma_f32_32x32x16_bf16 v[4:19], v[182:185], v[100:103], v[4:19]
	s_waitcnt vmcnt(26)
	v_mfma_f32_32x32x16_bf16 v[20:35], v[182:185], v[112:115], v[20:35]
	ds_read_b128 v[182:185], v180 offset:128
	global_load_dwordx4 v[100:103], v254, s[98:99] offset:3072
	s_waitcnt vmcnt(28) lgkmcnt(1)
	v_mfma_f32_32x32x16_bf16 v[4:19], v[186:189], v[104:107], v[4:19]
	s_waitcnt vmcnt(26)
	v_mfma_f32_32x32x16_bf16 v[20:35], v[186:189], v[108:111], v[20:35]
	ds_read_b128 v[186:189], v180 offset:160
	s_waitcnt vmcnt(24) lgkmcnt(1)
	v_mfma_f32_32x32x16_bf16 v[4:19], v[182:185], v[88:91], v[4:19]
	s_waitcnt vmcnt(23)
	v_mfma_f32_32x32x16_bf16 v[20:35], v[182:185], v[92:95], v[20:35]
	ds_read_b128 v[182:185], v180 offset:192
	s_waitcnt vmcnt(21) lgkmcnt(1)
	v_mfma_f32_32x32x16_bf16 v[4:19], v[186:189], v[96:99], v[4:19]
	s_waitcnt vmcnt(22)
	v_mfma_f32_32x32x16_bf16 v[20:35], v[186:189], v[84:87], v[20:35]
	ds_read_b128 v[186:189], v180 offset:224
	s_waitcnt vmcnt(20) lgkmcnt(1)
	v_mfma_f32_32x32x16_bf16 v[4:19], v[182:185], v[80:83], v[4:19]
	s_waitcnt vmcnt(17)
	v_mfma_f32_32x32x16_bf16 v[20:35], v[182:185], v[76:79], v[20:35]
	ds_read_b128 v[182:185], v180 offset:256
	s_waitcnt vmcnt(18) lgkmcnt(1)
	v_mfma_f32_32x32x16_bf16 v[4:19], v[186:189], v[72:75], v[4:19]
	s_waitcnt vmcnt(16)
	v_mfma_f32_32x32x16_bf16 v[20:35], v[186:189], v[68:71], v[20:35]
	ds_read_b128 v[186:189], v180 offset:288
	s_waitcnt vmcnt(15) lgkmcnt(1)
	v_mfma_f32_32x32x16_bf16 v[4:19], v[182:185], v[192:195], v[4:19]
	s_waitcnt vmcnt(14)
	v_mfma_f32_32x32x16_bf16 v[20:35], v[182:185], v[196:199], v[20:35]
	ds_read_b128 v[182:185], v180 offset:320
	s_waitcnt vmcnt(13) lgkmcnt(1)
	v_mfma_f32_32x32x16_bf16 v[4:19], v[186:189], v[200:203], v[4:19]
	s_waitcnt vmcnt(12)
	v_mfma_f32_32x32x16_bf16 v[20:35], v[186:189], v[204:207], v[20:35]
	ds_read_b128 v[186:189], v180 offset:352
	s_waitcnt vmcnt(11) lgkmcnt(1)
	v_mfma_f32_32x32x16_bf16 v[4:19], v[182:185], v[208:211], v[4:19]
	s_waitcnt vmcnt(10)
	v_mfma_f32_32x32x16_bf16 v[20:35], v[182:185], v[226:229], v[20:35]
	ds_read_b128 v[182:185], v180 offset:384
	s_waitcnt vmcnt(9) lgkmcnt(1)
	v_mfma_f32_32x32x16_bf16 v[4:19], v[186:189], v[230:233], v[4:19]
	s_waitcnt vmcnt(8)
	v_mfma_f32_32x32x16_bf16 v[20:35], v[186:189], v[234:237], v[20:35]
	ds_read_b128 v[186:189], v180 offset:416
	s_waitcnt vmcnt(7) lgkmcnt(1)
	v_mfma_f32_32x32x16_bf16 v[4:19], v[182:185], v[238:241], v[4:19]
	s_waitcnt vmcnt(6)
	v_mfma_f32_32x32x16_bf16 v[20:35], v[182:185], v[246:249], v[20:35]
	ds_read_b128 v[182:185], v180 offset:448
	s_waitcnt vmcnt(5) lgkmcnt(1)
	v_mfma_f32_32x32x16_bf16 v[4:19], v[186:189], v[250:253], v[4:19]
	s_waitcnt vmcnt(4)
	v_mfma_f32_32x32x16_bf16 v[20:35], v[186:189], v[124:127], v[20:35]
	ds_read_b128 v[186:189], v180 offset:480
	s_waitcnt vmcnt(3) lgkmcnt(1)
	v_mfma_f32_32x32x16_bf16 v[4:19], v[182:185], v[128:131], v[4:19]
	s_waitcnt vmcnt(2)
	v_mfma_f32_32x32x16_bf16 v[20:35], v[182:185], v[116:119], v[20:35]
	s_waitcnt vmcnt(1) lgkmcnt(0)
	v_mfma_f32_32x32x16_bf16 v[4:19], v[186:189], v[120:123], v[4:19]
	s_waitcnt vmcnt(0)
	v_mfma_f32_32x32x16_bf16 v[20:35], v[186:189], v[100:103], v[20:35]
	s_cmp_lg_u32 s31, s6
	s_cbranch_scc0 .LBB0_892
.LBB0_890:
	v_lshl_add_u64 v[162:163], s[82:83], 0, v[158:159]
	v_add_co_u32_e32 v68, vcc, s38, v162
	v_lshl_add_u64 v[164:165], s[82:83], 0, v[160:161]
	s_nop 0
	v_addc_co_u32_e32 v69, vcc, 0, v163, vcc
	v_add_co_u32_e32 v70, vcc, s39, v162
	s_add_i32 s6, s6, 1
	s_nop 0
	v_addc_co_u32_e32 v71, vcc, 0, v163, vcc
	v_add_co_u32_e32 v72, vcc, s38, v164
	s_cmp_ge_i32 s6, s31
	s_nop 0
	v_addc_co_u32_e32 v73, vcc, 0, v165, vcc
	v_add_co_u32_e32 v182, vcc, s39, v164
	s_nop 1
	v_addc_co_u32_e32 v183, vcc, 0, v165, vcc
	global_load_dwordx4 v[116:119], v[68:69], off offset:1024
	global_load_dwordx4 v[100:103], v[68:69], off offset:2048
	global_load_dwordx4 v[120:123], v[72:73], off offset:1024
	global_load_dwordx4 v[104:107], v[68:69], off offset:3072
	global_load_dwordx4 v[112:115], v[72:73], off offset:2048
	global_load_dwordx4 v[108:111], v[72:73], off offset:3072
	global_load_dwordx4 v[124:127], v[70:71], off offset:-4096
	global_load_dwordx4 v[88:91], v[70:71], off
	global_load_dwordx4 v[92:95], v[182:183], off
	global_load_dwordx4 v[84:87], v[182:183], off offset:1024
	global_load_dwordx4 v[96:99], v[70:71], off offset:1024
	global_load_dwordx4 v[80:83], v[70:71], off offset:2048
	global_load_dwordx4 v[128:131], v[182:183], off offset:-4096
	global_load_dwordx4 v[72:75], v[70:71], off offset:3072
	global_load_dwordx4 v[76:79], v[182:183], off offset:2048
	s_nop 0
	global_load_dwordx4 v[68:71], v[182:183], off offset:3072
	v_add_u32_e32 v242, 0x2000, v158
	v_add_u32_e32 v243, 0x2000, v160
	v_add_u32_e32 v245, 0x3000, v158
	v_add_u32_e32 v254, 0x3000, v160
	global_load_dwordx4 v[192:195], v242, s[98:99] offset:0
	global_load_dwordx4 v[196:199], v243, s[98:99] offset:0
	global_load_dwordx4 v[200:203], v242, s[98:99] offset:1024
	global_load_dwordx4 v[204:207], v243, s[98:99] offset:1024
	global_load_dwordx4 v[208:211], v242, s[98:99] offset:2048
	global_load_dwordx4 v[226:229], v243, s[98:99] offset:2048
	global_load_dwordx4 v[230:233], v242, s[98:99] offset:3072
	global_load_dwordx4 v[234:237], v243, s[98:99] offset:3072
	global_load_dwordx4 v[238:241], v245, s[98:99] offset:0
	global_load_dwordx4 v[246:249], v254, s[98:99] offset:0
	global_load_dwordx4 v[250:253], v245, s[98:99] offset:1024
	s_barrier
	s_waitcnt vmcnt(27)
	ds_write_b128 v132, v[36:39]
	ds_write_b128 v141, v[40:43]
	ds_write_b128 v174, v[44:47]
	ds_write_b128 v175, v[48:51]
	ds_write_b128 v176, v[52:55]
	ds_write_b128 v177, v[56:59]
	ds_write_b128 v178, v[60:63]
	ds_write_b128 v179, v[64:67]
	s_waitcnt lgkmcnt(0)
	s_barrier
	s_cbranch_scc1 .LBB0_889
	v_lshl_add_u64 v[36:37], s[82:83], 0, v[142:143]
	v_lshl_add_u64 v[40:41], s[82:83], 0, v[144:145]
	v_lshl_add_u64 v[44:45], s[82:83], 0, v[146:147]
	v_lshl_add_u64 v[48:49], s[82:83], 0, v[148:149]
	v_lshl_add_u64 v[52:53], s[82:83], 0, v[150:151]
	v_lshl_add_u64 v[56:57], s[82:83], 0, v[152:153]
	v_lshl_add_u64 v[60:61], s[82:83], 0, v[154:155]
	v_lshl_add_u64 v[64:65], s[82:83], 0, v[156:157]
	global_load_dwordx4 v[36:39], v[36:37], off
	s_nop 0
	global_load_dwordx4 v[40:43], v[40:41], off
	s_nop 0
	global_load_dwordx4 v[44:47], v[44:45], off
	s_nop 0
	global_load_dwordx4 v[48:51], v[48:49], off
	s_nop 0
	global_load_dwordx4 v[52:55], v[52:53], off
	s_nop 0
	global_load_dwordx4 v[56:59], v[56:57], off
	s_nop 0
	global_load_dwordx4 v[60:63], v[60:61], off
	s_nop 0
	global_load_dwordx4 v[64:67], v[64:65], off
.Lskd_more0:
	v_lshl_add_u64 v[142:143], v[142:143], 0, s[26:27]
	v_lshl_add_u64 v[144:145], v[144:145], 0, s[26:27]
	v_lshl_add_u64 v[146:147], v[146:147], 0, s[26:27]
	v_lshl_add_u64 v[148:149], v[148:149], 0, s[26:27]
	v_lshl_add_u64 v[150:151], v[150:151], 0, s[26:27]
	v_lshl_add_u64 v[152:153], v[152:153], 0, s[26:27]
	v_lshl_add_u64 v[154:155], v[154:155], 0, s[26:27]
	v_lshl_add_u64 v[156:157], v[156:157], 0, s[26:27]
	v_lshl_add_u64 v[158:159], v[158:159], 0, s[28:29]
	v_lshl_add_u64 v[160:161], v[160:161], 0, s[28:29]
	ds_read_b128 v[182:185], v180
	ds_read_b128 v[186:189], v180 offset:32
	s_waitcnt vmcnt(28) lgkmcnt(1)
	v_mfma_f32_32x32x16_bf16 v[4:19], v[182:185], v[124:127], v[4:19]
	s_waitcnt vmcnt(22)
	v_mfma_f32_32x32x16_bf16 v[20:35], v[182:185], v[128:131], v[20:35]
	ds_read_b128 v[182:185], v180 offset:64
	global_load_dwordx4 v[124:127], v254, s[98:99] offset:1024
	global_load_dwordx4 v[128:131], v245, s[98:99] offset:2048
	s_waitcnt vmcnt(36) lgkmcnt(1)
	v_mfma_f32_32x32x16_bf16 v[4:19], v[186:189], v[116:119], v[4:19]
	s_waitcnt vmcnt(34)
	v_mfma_f32_32x32x16_bf16 v[20:35], v[186:189], v[120:123], v[20:35]
	ds_read_b128 v[186:189], v180 offset:96
	global_load_dwordx4 v[116:119], v254, s[98:99] offset:2048
	global_load_dwordx4 v[120:123], v245, s[98:99] offset:3072
	s_waitcnt vmcnt(37) lgkmcnt(1)
	v_mfma_f32_32x32x16_bf16 v[4:19], v[182:185], v[100:103], v[4:19]
	s_waitcnt vmcnt(34)
	v_mfma_f32_32x32x16_bf16 v[20:35], v[182:185], v[112:115], v[20:35]
	ds_read_b128 v[182:185], v180 offset:128
	global_load_dwordx4 v[100:103], v254, s[98:99] offset:3072
	s_waitcnt vmcnt(36) lgkmcnt(1)
	v_mfma_f32_32x32x16_bf16 v[4:19], v[186:189], v[104:107], v[4:19]
	s_waitcnt vmcnt(34)
	v_mfma_f32_32x32x16_bf16 v[20:35], v[186:189], v[108:111], v[20:35]
	ds_read_b128 v[186:189], v180 offset:160
	s_waitcnt vmcnt(32) lgkmcnt(1)
	v_mfma_f32_32x32x16_bf16 v[4:19], v[182:185], v[88:91], v[4:19]
	s_waitcnt vmcnt(31)
	v_mfma_f32_32x32x16_bf16 v[20:35], v[182:185], v[92:95], v[20:35]
	ds_read_b128 v[182:185], v180 offset:192
	s_waitcnt vmcnt(29) lgkmcnt(1)
	v_mfma_f32_32x32x16_bf16 v[4:19], v[186:189], v[96:99], v[4:19]
	s_waitcnt vmcnt(30)
	v_mfma_f32_32x32x16_bf16 v[20:35], v[186:189], v[84:87], v[20:35]
	ds_read_b128 v[186:189], v180 offset:224
	s_waitcnt vmcnt(28) lgkmcnt(1)
	v_mfma_f32_32x32x16_bf16 v[4:19], v[182:185], v[80:83], v[4:19]
	s_waitcnt vmcnt(25)
	v_mfma_f32_32x32x16_bf16 v[20:35], v[182:185], v[76:79], v[20:35]
	ds_read_b128 v[182:185], v180 offset:256
	s_waitcnt vmcnt(26) lgkmcnt(1)
	v_mfma_f32_32x32x16_bf16 v[4:19], v[186:189], v[72:75], v[4:19]
	s_waitcnt vmcnt(24)
	v_mfma_f32_32x32x16_bf16 v[20:35], v[186:189], v[68:71], v[20:35]
	ds_read_b128 v[186:189], v180 offset:288
	s_waitcnt vmcnt(23) lgkmcnt(1)
	v_mfma_f32_32x32x16_bf16 v[4:19], v[182:185], v[192:195], v[4:19]
	s_waitcnt vmcnt(22)
	v_mfma_f32_32x32x16_bf16 v[20:35], v[182:185], v[196:199], v[20:35]
	ds_read_b128 v[182:185], v180 offset:320
	s_waitcnt vmcnt(21) lgkmcnt(1)
	v_mfma_f32_32x32x16_bf16 v[4:19], v[186:189], v[200:203], v[4:19]
	s_waitcnt vmcnt(20)
	v_mfma_f32_32x32x16_bf16 v[20:35], v[186:189], v[204:207], v[20:35]
	ds_read_b128 v[186:189], v180 offset:352
	s_waitcnt vmcnt(19) lgkmcnt(1)
	v_mfma_f32_32x32x16_bf16 v[4:19], v[182:185], v[208:211], v[4:19]
	s_waitcnt vmcnt(18)
	v_mfma_f32_32x32x16_bf16 v[20:35], v[182:185], v[226:229], v[20:35]
	ds_read_b128 v[182:185], v180 offset:384
	s_waitcnt vmcnt(17) lgkmcnt(1)
	v_mfma_f32_32x32x16_bf16 v[4:19], v[186:189], v[230:233], v[4:19]
	s_waitcnt vmcnt(16)
	v_mfma_f32_32x32x16_bf16 v[20:35], v[186:189], v[234:237], v[20:35]
	ds_read_b128 v[186:189], v180 offset:416
	s_waitcnt vmcnt(15) lgkmcnt(1)
	v_mfma_f32_32x32x16_bf16 v[4:19], v[182:185], v[238:241], v[4:19]
	s_waitcnt vmcnt(14)
	v_mfma_f32_32x32x16_bf16 v[20:35], v[182:185], v[246:249], v[20:35]
	ds_read_b128 v[182:185], v180 offset:448
	s_waitcnt vmcnt(13) lgkmcnt(1)
	v_mfma_f32_32x32x16_bf16 v[4:19], v[186:189], v[250:253], v[4:19]
	s_waitcnt vmcnt(4)
	v_mfma_f32_32x32x16_bf16 v[20:35], v[186:189], v[124:127], v[20:35]
	ds_read_b128 v[186:189], v180 offset:480
	s_waitcnt vmcnt(3) lgkmcnt(1)
	v_mfma_f32_32x32x16_bf16 v[4:19], v[182:185], v[128:131], v[4:19]
	s_waitcnt vmcnt(2)
	v_mfma_f32_32x32x16_bf16 v[20:35], v[182:185], v[116:119], v[20:35]
	s_waitcnt vmcnt(1) lgkmcnt(0)
	v_mfma_f32_32x32x16_bf16 v[4:19], v[186:189], v[120:123], v[4:19]
	s_waitcnt vmcnt(0)
	v_mfma_f32_32x32x16_bf16 v[20:35], v[186:189], v[100:103], v[20:35]
	s_cmp_lg_u32 s31, s6
	s_cbranch_scc0 .LBB0_892
	s_branch .LBB0_890

	.amdhsa_kernel _Z8yoco_fwd6Params
		.amdhsa_group_segment_fixed_size 0
		.amdhsa_private_segment_fixed_size 0
		.amdhsa_kernarg_size 472
		.amdhsa_user_sgpr_count 2
		.amdhsa_user_sgpr_dispatch_ptr 0
		.amdhsa_user_sgpr_queue_ptr 0
		.amdhsa_user_sgpr_kernarg_segment_ptr 1
		.amdhsa_user_sgpr_dispatch_id 0
		.amdhsa_user_sgpr_kernarg_preload_length 0
		.amdhsa_user_sgpr_kernarg_preload_offset 0
		.amdhsa_user_sgpr_private_segment_size 0
		.amdhsa_uses_dynamic_stack 0
		.amdhsa_enable_private_segment 0
		.amdhsa_system_sgpr_workgroup_id_x 1
		.amdhsa_system_sgpr_workgroup_id_y 0
		.amdhsa_system_sgpr_workgroup_id_z 0
		.amdhsa_system_sgpr_workgroup_info 0
		.amdhsa_system_vgpr_workitem_id 2
		.amdhsa_next_free_vgpr 256
		.amdhsa_next_free_sgpr 102
		.amdhsa_accum_offset 256
		.amdhsa_reserve_vcc 1
		.amdhsa_float_round_mode_32 0
		.amdhsa_float_round_mode_16_64 0
		.amdhsa_float_denorm_mode_32 3
		.amdhsa_float_denorm_mode_16_64 3
		.amdhsa_dx10_clamp 1
		.amdhsa_ieee_mode 1
		.amdhsa_fp16_overflow 0
		.amdhsa_tg_split 0
		.amdhsa_exception_fp_ieee_invalid_op 0
		.amdhsa_exception_fp_denorm_src 0
		.amdhsa_exception_fp_ieee_div_zero 0
		.amdhsa_exception_fp_ieee_overflow 0
		.amdhsa_exception_fp_ieee_underflow 0
		.amdhsa_exception_fp_ieee_inexact 0
		.amdhsa_exception_int_div_zero 0
	.end_amdhsa_kernel

amdhsa.kernels:
  - .agpr_count:     0
    .args:
      - .offset:         0
        .size:           216
        .value_kind:     by_value
      - .offset:         216
        .size:           4
        .value_kind:     hidden_block_count_x
      - .offset:         220
        .size:           4
        .value_kind:     hidden_block_count_y
      - .offset:         224
        .size:           4
        .value_kind:     hidden_block_count_z
      - .offset:         228
        .size:           2
        .value_kind:     hidden_group_size_x
      - .offset:         230
        .size:           2
        .value_kind:     hidden_group_size_y
      - .offset:         232
        .size:           2
        .value_kind:     hidden_group_size_z
      - .offset:         234
        .size:           2
        .value_kind:     hidden_remainder_x
      - .offset:         236
        .size:           2
        .value_kind:     hidden_remainder_y
      - .offset:         238
        .size:           2
        .value_kind:     hidden_remainder_z
      - .offset:         256
        .size:           8
        .value_kind:     hidden_global_offset_x
      - .offset:         264
        .size:           8
        .value_kind:     hidden_global_offset_y
      - .offset:         272
        .size:           8
        .value_kind:     hidden_global_offset_z
      - .offset:         280
        .size:           2
        .value_kind:     hidden_grid_dims
      - .offset:         304
        .size:           8
        .value_kind:     hidden_multigrid_sync_arg
      - .offset:         336
        .size:           4
        .value_kind:     hidden_dynamic_lds_size
    .group_segment_fixed_size: 0
    .kernarg_segment_align: 8
    .kernarg_segment_size: 472
    .language:       OpenCL C
    .language_version:
      - 2
      - 0
    .max_flat_workgroup_size: 512
    .name:           _Z8yoco_fwd6Params
    .private_segment_fixed_size: 0
    .sgpr_count:     108
    .sgpr_spill_count: 56
    .symbol:         _Z8yoco_fwd6Params.kd
    .uniform_work_group_size: 1
    .uses_dynamic_stack: false
    .vgpr_count:     256
    .vgpr_spill_count: 0
    .wavefront_size: 64
